# scan entry: non-proj preamble runs before the tile-completion gate wait; GLA heavy blocks leave the queue at head>=128
# speedup vs baseline: 1.0444x; 1.0073x over previous
.LBB0_226:
	v_writelane_b32 v254, s28, 36
	s_nop 1
	v_writelane_b32 v254, s29, 37
	v_writelane_b32 v254, s26, 38
	s_nop 1
	v_writelane_b32 v254, s27, 39
	v_writelane_b32 v254, s99, 40
	s_or_b64 exec, exec, s[0:1]
	s_cmpk_gt_i32 s2, 0x7f
	s_cselect_b64 s[0:1], -1, 0
	s_and_b32 s10, s2, 7
	s_ashr_i32 s97, s2, 3
	s_lshl_b32 s3, s10, 6
	s_lshl_b32 s4, s10, 8
	s_add_u32 s4, s88, s4
	s_addc_u32 s5, s89, 0
	s_add_u32 s8, s4, 0x3700
	s_addc_u32 s9, s5, 0
	s_lshl_b32 s6, s10, 4
	s_or_b32 s13, s6, s97
	s_cmp_gt_i32 s2, 63
	s_movk_i32 s2, 0x80
	s_cselect_b32 s2, s2, 0x110
	v_writelane_b32 v254, s2, 41
	s_movk_i32 s2, 0x80
	s_cselect_b32 s7, s2, 0x90
	s_cselect_b32 s14, 0x90, s2
	s_add_u32 s16, s8, s7
	v_writelane_b32 v254, s8, 34
	s_addc_u32 s17, s9, 0
	s_add_i32 s2, s6, 64
	v_writelane_b32 v254, s9, 35
	v_writelane_b32 v254, s2, 42
	v_writelane_b32 v254, s10, 43
	s_lshl_b32 s2, s10, 3
	v_writelane_b32 v254, s2, 44
	s_add_i32 s2, s3, 0x80
	v_writelane_b32 v254, s2, 45
	s_add_u32 s2, s4, 0x37a0
	s_addc_u32 s3, s5, 0
	v_writelane_b32 v254, s2, 46
	s_mov_b32 s77, 0
	v_mov_b32_e32 v3, 0
	v_writelane_b32 v254, s3, 47
	s_add_u32 s2, s42, 0x1000
	s_addc_u32 s3, s43, 0
	v_writelane_b32 v254, s2, 48
	s_add_i32 s15, 16, 0x11604
	s_add_i32 s18, 16, 0x11600
	v_writelane_b32 v254, s3, 49
	v_writelane_b32 v254, s13, 50
	v_writelane_b32 v254, s14, 51
	v_writelane_b32 v254, s16, 52
	s_movk_i32 s29, 0x1840
	s_movk_i32 s30, 0x70
	v_writelane_b32 v254, s17, 53
	s_mov_b64 s[98:99], 0x30800
	s_add_i32 s31, 16, 0x11000
	s_mov_b32 s33, 0x5040100
	s_mov_b32 s72, 0x7060302
	s_mov_b32 s73, 0xbfb8aa3b
	s_mov_b32 s66, 0x800000
	s_mov_b32 s67, 0x3f317217
	s_mov_b32 s70, 0x7f800000
	s_mov_b32 s96, 0x3d800000
	v_mov_b32_e32 v106, 2.0
	s_movk_i32 s19, 0xc20
	v_mov_b32_e32 v136, s18
	v_mov_b32_e32 v137, 0x61000
	v_mov_b32_e32 v138, 0x41b17218
	v_mbcnt_hi_u32_b32 v1, -1, v1
	v_writelane_b32 v254, s15, 54
	s_waitcnt lgkmcnt(0)
	s_barrier
	v_writelane_b32 v254, s18, 55
	s_branch .LBB0_230

.LBB0_264:
	v_mov_b32_e32 v98, v0
	v_writelane_b32 v254, s2, 56
	v_writelane_b32 v254, s3, 57
	v_writelane_b32 v254, s11, 58

.LBB0_285:
	s_or_b64 exec, exec, s[4:5]
	s_lshl_b32 s4, s9, 11
	s_add_i32 s10, s4, 0x2000
	s_lshl_b32 s9, s9, 8
	s_and_b64 s[4:5], s[2:3], exec
	s_cselect_b32 s57, s10, s9
	s_and_b64 s[4:5], exec, s[38:39]
	v_ashrrev_i32_e32 v92, 3, v98
	v_lshlrev_b32_e32 v122, 1, v98
	v_ashrrev_i32_e32 v4, 2, v98
	v_lshlrev_b32_e32 v120, 4, v100
	s_movk_i32 s4, 0x400
	v_add_u32_e32 v2, s57, v92
	v_and_or_b32 v55, v122, 62, s57
	v_and_b32_e32 v56, -8, v4
	v_add_u32_e32 v4, s57, v120
	v_mov_b64_e32 v[58:59], s[50:51]
	s_cselect_b32 s9, s4, 0x1000
	v_or_b32_e32 v62, v4, v99
	v_mad_i64_i32 v[4:5], s[4:5], v2, s29, v[58:59]
	v_mad_i64_i32 v[60:61], s[4:5], v55, s29, v[58:59]
	s_lshl_b32 s4, s8, 8
	s_or_b32 s76, s4, s9
	v_ashrrev_i32_e32 v57, 31, v56
	v_lshlrev_b32_e32 v91, 4, v98
	v_lshl_add_u64 v[60:61], v[60:61], 0, s[76:77]
	v_and_b32_e32 v2, 0x70, v91
	v_lshl_add_u64 v[112:113], v[56:57], 1, v[60:61]
	v_mad_i64_i32 v[56:57], s[4:5], v62, s29, v[58:59]
	s_lshl_b32 s76, s6, 5
	v_lshl_add_u64 v[4:5], v[4:5], 0, v[2:3]
	v_lshl_add_u64 v[56:57], v[56:57], 0, s[76:77]
	v_lshlrev_b32_e32 v2, 1, v54
	v_lshl_add_u64 v[54:55], v[56:57], 0, v[2:3]
	s_mov_b64 s[4:5], 0x1800
	s_and_b64 s[2:3], s[2:3], exec
	v_lshl_add_u64 v[114:115], v[54:55], 0, s[4:5]
	s_cselect_b32 s71, 32, 4
	s_or_b32 s4, s7, 0x600
	v_writelane_b32 v254, s38, 20
	s_and_b64 s[2:3], exec, s[38:39]
	s_movk_i32 s2, 0x100
	s_cselect_b32 s8, s7, s4
	s_cselect_b32 s9, s2, 0x700
	s_add_i32 s10, s71, -1
	s_cmp_eq_u32 s6, 0
	s_cselect_b64 s[2:3], -1, 0
	s_and_b64 s[4:5], s[2:3], exec
	v_writelane_b32 v254, s39, 21
	s_cselect_b32 s38, 0, s10
	s_or_b32 s6, s9, s7
	v_mad_u64_u32 v[54:55], s[4:5], s38, v137, v[4:5]
	s_lshl_b32 s76, s8, 1
	s_lshl_b32 s68, s6, 1
	s_mov_b32 s69, s77
	v_lshl_add_u64 v[56:57], v[54:55], 0, s[76:77]
	v_lshl_add_u64 v[58:59], v[54:55], 0, s[68:69]
	v_lshl_add_u64 v[54:55], v[54:55], 0, s[98:99]
	v_readlane_b32 s6, v254, 56
	v_readlane_b32 s7, v254, 57
	v_readlane_b32 s8, v254, 58
	s_cmp_eq_u64 s[6:7], 0
	s_cbranch_scc1 .Lgate_done
	v_cmp_eq_u32_e32 vcc, 0, v0
	s_and_saveexec_b64 s[10:11], vcc
	s_cbranch_execz .Lgate_join
	v_mov_b32_e32 v230, 0
	s_mov_b32 s9, 0x400001
.Lgate_poll:
	global_load_dword v231, v230, s[6:7] sc1
	s_waitcnt vmcnt(0)
	v_readfirstlane_b32 s4, v231
	s_cmp_ge_u32 s4, s8
	s_cbranch_scc1 .Lgate_ok
	s_sleep 4
	s_add_i32 s9, s9, -1
	s_cmp_eq_u32 s9, 0
	s_cbranch_scc0 .Lgate_poll

.Lgate_join:
	s_or_b64 exec, exec, s[10:11]
	s_barrier
.Lgate_done:
	global_load_dwordx4 v[86:89], v[56:57], off
	global_load_dwordx4 v[82:85], v[58:59], off
	v_lshl_add_u64 v[56:57], v[54:55], 0, s[76:77]
	v_lshl_add_u64 v[54:55], v[54:55], 0, s[68:69]
	global_load_dwordx4 v[78:81], v[56:57], off
	global_load_dwordx4 v[74:77], v[54:55], off
	v_mad_u64_u32 v[54:55], s[4:5], s38, v137, v[112:113]
	v_add_co_u32_e32 v56, vcc, 0x1000, v54
	v_lshlrev_b32_e32 v2, 7, v92
	s_nop 0
	v_addc_co_u32_e32 v57, vcc, 0, v55, vcc
	global_load_dwordx4 v[66:69], v[54:55], off
	global_load_dwordx4 v[58:61], v[54:55], off offset:128
	global_load_dwordx4 v[70:73], v[56:57], off offset:2112
	global_load_dwordx4 v[62:65], v[56:57], off offset:2240
	v_mad_u64_u32 v[54:55], s[4:5], s38, v137, v[114:115]
	global_load_dwordx4 v[54:57], v[54:55], off
	v_xor_b32_e32 v91, v91, v98
	v_and_or_b32 v2, v91, s30, v2
	v_cndmask_b32_e64 v91, 0, 1, s[0:1]
	s_mov_b64 s[6:7], -1
	v_cmp_ne_u32_e64 s[4:5], 1, v91
	s_andn2_b64 vcc, exec, s[0:1]
	v_add_u32_e32 v156, 16, v2
	s_cbranch_vccnz .LBB0_287
	s_mov_b64 s[6:7], 0
	s_waitcnt vmcnt(8)
	ds_write_b128 v156, v[86:89]
	s_waitcnt vmcnt(7)
	ds_write_b128 v156, v[82:85] offset:8192
	s_waitcnt vmcnt(6)
	ds_write_b128 v156, v[78:81] offset:4096
	s_waitcnt vmcnt(5)
	ds_write_b128 v156, v[74:77] offset:12288
